# side-job-free copies of the P1 int8 and P4 K-loops, used once a wave's column-max range is used up (left == 0)
# speedup vs baseline: 1.0070x; 1.0070x over previous
.Lp1i_body:
	s_add_i32 s8, s74, 2
	s_add_u32 s34, s30, 0xfff80080
	s_addc_u32 s35, s31, -1
	s_cmp_eq_u32 s71, s74
	s_cselect_b32 s37, s67, s35
	s_cselect_b32 s36, s68, s34
	s_cselect_b32 s35, s69, s73
	s_cselect_b32 s34, s70, s72
	v_add_u32_e32 v5, s57, v177
	ds_read_b128 v[160:163], v5
	ds_read_b128 v[164:167], v5 offset:1024
	ds_read_b128 v[168:171], v5 offset:2048
	ds_read_b128 v[182:185], v5 offset:3072
	v_add_u32_e32 v5, s58, v177
	ds_read_b128 v[186:189], v5
	ds_read_b128 v[190:193], v5 offset:1024
	ds_read_b128 v[194:197], v5 offset:2048
	ds_read_b128 v[198:201], v5 offset:3072
	v_lshl_add_u64 v[6:7], s[30:31], 0, v[146:147]
	s_add_i32 m0, s46, 0xc000
	ds_read_b128 v[202:205], v180
	ds_read_b128 v[206:209], v180 offset:1024
	ds_read_b128 v[210:213], v180 offset:2048
	ds_read_b128 v[214:217], v180 offset:3072
	ds_read_b128 v[218:221], v180 offset:4096
	ds_read_b128 v[222:225], v180 offset:5120
	ds_read_b128 v[226:229], v180 offset:6144
	ds_read_b128 v[230:233], v180 offset:7168
	global_load_lds_dwordx4 v[6:7], off
	v_lshl_add_u64 v[6:7], s[30:31], 0, v[148:149]
	s_add_i32 m0, s46, 0xe000
	s_nop 0
	global_load_lds_dwordx4 v[6:7], off
	s_waitcnt vmcnt(8)
	s_waitcnt lgkmcnt(0)
	s_barrier
	s_setprio 1
	s_waitcnt lgkmcnt(0)
	v_mfma_i32_16x16x64_i8 v[132:135], v[160:163], v[202:205], v[132:135]
	v_mfma_i32_16x16x64_i8 v[128:131], v[168:171], v[202:205], v[128:131]
	v_mfma_i32_16x16x64_i8 v[124:127], v[160:163], v[210:213], v[124:127]
	v_mfma_i32_16x16x64_i8 v[120:123], v[168:171], v[210:213], v[120:123]
	v_mfma_i32_16x16x64_i8 v[112:115], v[160:163], v[218:221], v[112:115]
	v_mfma_i32_16x16x64_i8 v[104:107], v[168:171], v[218:221], v[104:107]
	v_mfma_i32_16x16x64_i8 v[96:99], v[160:163], v[226:229], v[96:99]
	v_mfma_i32_16x16x64_i8 v[88:91], v[168:171], v[226:229], v[88:91]
	v_mfma_i32_16x16x64_i8 v[132:135], v[164:167], v[206:209], v[132:135]
	v_mfma_i32_16x16x64_i8 v[128:131], v[182:185], v[206:209], v[128:131]
	v_mfma_i32_16x16x64_i8 v[124:127], v[164:167], v[214:217], v[124:127]
	v_mfma_i32_16x16x64_i8 v[120:123], v[182:185], v[214:217], v[120:123]
	v_mfma_i32_16x16x64_i8 v[112:115], v[164:167], v[222:225], v[112:115]
	v_mfma_i32_16x16x64_i8 v[104:107], v[182:185], v[222:225], v[104:107]
	v_mfma_i32_16x16x64_i8 v[96:99], v[164:167], v[230:233], v[96:99]
	v_mfma_i32_16x16x64_i8 v[88:91], v[182:185], v[230:233], v[88:91]
	s_setprio 0
	s_setprio 1
	v_mfma_i32_16x16x64_i8 v[116:119], v[186:189], v[202:205], v[116:119]
	v_mfma_i32_16x16x64_i8 v[108:111], v[194:197], v[202:205], v[108:111]
	v_mfma_i32_16x16x64_i8 v[100:103], v[186:189], v[210:213], v[100:103]
	v_mfma_i32_16x16x64_i8 v[92:95], v[194:197], v[210:213], v[92:95]
	v_mfma_i32_16x16x64_i8 v[84:87], v[186:189], v[218:221], v[84:87]
	v_mfma_i32_16x16x64_i8 v[80:83], v[194:197], v[218:221], v[80:83]
	v_mfma_i32_16x16x64_i8 v[76:79], v[186:189], v[226:229], v[76:79]
	v_mfma_i32_16x16x64_i8 v[72:75], v[194:197], v[226:229], v[72:75]
	v_mfma_i32_16x16x64_i8 v[116:119], v[190:193], v[206:209], v[116:119]
	v_mfma_i32_16x16x64_i8 v[108:111], v[198:201], v[206:209], v[108:111]
	v_mfma_i32_16x16x64_i8 v[100:103], v[190:193], v[214:217], v[100:103]
	v_mfma_i32_16x16x64_i8 v[92:95], v[198:201], v[214:217], v[92:95]
	v_mfma_i32_16x16x64_i8 v[84:87], v[190:193], v[222:225], v[84:87]
	v_mfma_i32_16x16x64_i8 v[80:83], v[198:201], v[222:225], v[80:83]
	v_mfma_i32_16x16x64_i8 v[76:79], v[190:193], v[230:233], v[76:79]
	v_mfma_i32_16x16x64_i8 v[72:75], v[198:201], v[230:233], v[72:75]
	s_setprio 0
	s_barrier
	s_add_i32 s74, s57, s45
	v_lshl_add_u64 v[236:237], s[34:35], 0, v[138:139]
	s_mov_b32 m0, s74
	ds_read_b128 v[202:205], v180 offset:16384
	ds_read_b128 v[206:209], v180 offset:17408
	ds_read_b128 v[210:213], v180 offset:18432
	ds_read_b128 v[214:217], v180 offset:19456
	ds_read_b128 v[218:221], v180 offset:20480
	ds_read_b128 v[222:225], v180 offset:21504
	ds_read_b128 v[226:229], v180 offset:22528
	ds_read_b128 v[230:233], v180 offset:23552
	global_load_lds_dwordx4 v[236:237], off
	s_add_i32 m0, s74, 0x2000
	s_add_u32 s74, s34, 0x80000
	v_lshl_add_u64 v[238:239], s[34:35], 0, v[142:143]
	s_addc_u32 s75, s35, 0
	s_add_i32 s76, s58, s45
	global_load_lds_dwordx4 v[238:239], off
	v_lshl_add_u64 v[6:7], s[74:75], 0, v[138:139]
	s_mov_b32 m0, s76
	v_lshl_add_u64 v[240:241], s[36:37], 0, v[136:137]
	global_load_lds_dwordx4 v[6:7], off
	v_lshl_add_u64 v[6:7], s[74:75], 0, v[142:143]
	s_add_i32 m0, s76, 0x2000
	v_lshl_add_u64 v[242:243], s[36:37], 0, v[140:141]
	global_load_lds_dwordx4 v[6:7], off
	s_mov_b32 m0, s46
	s_nop 0
	global_load_lds_dwordx4 v[240:241], off
	s_mov_b32 m0, s47
	s_nop 0
	global_load_lds_dwordx4 v[242:243], off
	s_waitcnt vmcnt(8)
	s_waitcnt lgkmcnt(0)
	s_barrier
	s_setprio 1
	s_waitcnt lgkmcnt(0)
	v_mfma_i32_16x16x64_i8 v[68:71], v[160:163], v[202:205], v[68:71]
	v_mfma_i32_16x16x64_i8 v[64:67], v[168:171], v[202:205], v[64:67]
	v_mfma_i32_16x16x64_i8 v[60:63], v[160:163], v[210:213], v[60:63]
	v_mfma_i32_16x16x64_i8 v[56:59], v[168:171], v[210:213], v[56:59]
	v_mfma_i32_16x16x64_i8 v[48:51], v[160:163], v[218:221], v[48:51]
	v_mfma_i32_16x16x64_i8 v[40:43], v[168:171], v[218:221], v[40:43]
	v_mfma_i32_16x16x64_i8 v[32:35], v[160:163], v[226:229], v[32:35]
	v_mfma_i32_16x16x64_i8 v[24:27], v[168:171], v[226:229], v[24:27]
	v_mfma_i32_16x16x64_i8 v[68:71], v[164:167], v[206:209], v[68:71]
	v_mfma_i32_16x16x64_i8 v[64:67], v[182:185], v[206:209], v[64:67]
	v_mfma_i32_16x16x64_i8 v[60:63], v[164:167], v[214:217], v[60:63]
	v_mfma_i32_16x16x64_i8 v[56:59], v[182:185], v[214:217], v[56:59]
	v_mfma_i32_16x16x64_i8 v[48:51], v[164:167], v[222:225], v[48:51]
	v_mfma_i32_16x16x64_i8 v[40:43], v[182:185], v[222:225], v[40:43]
	v_mfma_i32_16x16x64_i8 v[32:35], v[164:167], v[230:233], v[32:35]
	v_mfma_i32_16x16x64_i8 v[24:27], v[182:185], v[230:233], v[24:27]
	s_setprio 0
	s_setprio 1
	v_mfma_i32_16x16x64_i8 v[52:55], v[186:189], v[202:205], v[52:55]
	v_mfma_i32_16x16x64_i8 v[44:47], v[194:197], v[202:205], v[44:47]
	v_mfma_i32_16x16x64_i8 v[36:39], v[186:189], v[210:213], v[36:39]
	v_mfma_i32_16x16x64_i8 v[28:31], v[194:197], v[210:213], v[28:31]
	v_mfma_i32_16x16x64_i8 v[20:23], v[186:189], v[218:221], v[20:23]
	v_mfma_i32_16x16x64_i8 v[16:19], v[194:197], v[218:221], v[16:19]
	v_mfma_i32_16x16x64_i8 v[12:15], v[186:189], v[226:229], v[12:15]
	v_mfma_i32_16x16x64_i8 v[6:9], v[194:197], v[226:229], v[8:11]
	v_mfma_i32_16x16x64_i8 v[52:55], v[190:193], v[206:209], v[52:55]
	v_mfma_i32_16x16x64_i8 v[44:47], v[198:201], v[206:209], v[44:47]
	v_mfma_i32_16x16x64_i8 v[36:39], v[190:193], v[214:217], v[36:39]
	v_mfma_i32_16x16x64_i8 v[28:31], v[198:201], v[214:217], v[28:31]
	v_mfma_i32_16x16x64_i8 v[20:23], v[190:193], v[222:225], v[20:23]
	v_mfma_i32_16x16x64_i8 v[16:19], v[198:201], v[222:225], v[16:19]
	v_mfma_i32_16x16x64_i8 v[12:15], v[190:193], v[230:233], v[12:15]
	v_mfma_i32_16x16x64_i8 v[6:9], v[198:201], v[230:233], v[6:9]
	s_setprio 0
	s_barrier
	s_add_i32 s74, 0, 0x18000
	v_add_u32_e32 v5, s74, v177
	s_add_i32 s75, 0, 0x1c000
	ds_read_b128 v[160:163], v5
	ds_read_b128 v[164:167], v5 offset:1024
	ds_read_b128 v[168:171], v5 offset:2048
	ds_read_b128 v[182:185], v5 offset:3072
	v_add_u32_e32 v5, s75, v177
	ds_read_b128 v[186:189], v5
	ds_read_b128 v[190:193], v5 offset:1024
	ds_read_b128 v[194:197], v5 offset:2048
	ds_read_b128 v[198:201], v5 offset:3072
	s_add_u32 s36, s36, 0x80000
	s_addc_u32 s37, s37, 0
	s_mov_b32 m0, s48
	v_lshl_add_u64 v[10:11], s[36:37], 0, v[136:137]
	ds_read_b128 v[202:205], v180 offset:32768
	ds_read_b128 v[206:209], v180 offset:33792
	ds_read_b128 v[210:213], v180 offset:34816
	ds_read_b128 v[214:217], v180 offset:35840
	ds_read_b128 v[218:221], v180 offset:36864
	ds_read_b128 v[222:225], v180 offset:37888
	ds_read_b128 v[226:229], v180 offset:38912
	ds_read_b128 v[230:233], v180 offset:39936
	global_load_lds_dwordx4 v[10:11], off
	v_lshl_add_u64 v[10:11], s[36:37], 0, v[140:141]
	s_mov_b32 m0, s49
	s_nop 0
	global_load_lds_dwordx4 v[10:11], off
	s_waitcnt vmcnt(8)
	s_waitcnt lgkmcnt(0)
	s_barrier
	s_setprio 1
	s_waitcnt lgkmcnt(0)
	v_mfma_i32_16x16x64_i8 v[132:135], v[160:163], v[202:205], v[132:135]
	v_mfma_i32_16x16x64_i8 v[128:131], v[168:171], v[202:205], v[128:131]
	v_mfma_i32_16x16x64_i8 v[124:127], v[160:163], v[210:213], v[124:127]
	v_mfma_i32_16x16x64_i8 v[120:123], v[168:171], v[210:213], v[120:123]
	v_mfma_i32_16x16x64_i8 v[112:115], v[160:163], v[218:221], v[112:115]
	v_mfma_i32_16x16x64_i8 v[104:107], v[168:171], v[218:221], v[104:107]
	v_mfma_i32_16x16x64_i8 v[96:99], v[160:163], v[226:229], v[96:99]
	v_mfma_i32_16x16x64_i8 v[88:91], v[168:171], v[226:229], v[88:91]
	v_mfma_i32_16x16x64_i8 v[132:135], v[164:167], v[206:209], v[132:135]
	v_mfma_i32_16x16x64_i8 v[128:131], v[182:185], v[206:209], v[128:131]
	v_mfma_i32_16x16x64_i8 v[124:127], v[164:167], v[214:217], v[124:127]
	v_mfma_i32_16x16x64_i8 v[120:123], v[182:185], v[214:217], v[120:123]
	v_mfma_i32_16x16x64_i8 v[112:115], v[164:167], v[222:225], v[112:115]
	v_mfma_i32_16x16x64_i8 v[104:107], v[182:185], v[222:225], v[104:107]
	v_mfma_i32_16x16x64_i8 v[96:99], v[164:167], v[230:233], v[96:99]
	v_mfma_i32_16x16x64_i8 v[88:91], v[182:185], v[230:233], v[88:91]
	s_setprio 0
	s_setprio 1
	v_mfma_i32_16x16x64_i8 v[116:119], v[186:189], v[202:205], v[116:119]
	v_mfma_i32_16x16x64_i8 v[108:111], v[194:197], v[202:205], v[108:111]
	v_mfma_i32_16x16x64_i8 v[100:103], v[186:189], v[210:213], v[100:103]
	v_mfma_i32_16x16x64_i8 v[92:95], v[194:197], v[210:213], v[92:95]
	v_mfma_i32_16x16x64_i8 v[84:87], v[186:189], v[218:221], v[84:87]
	v_mfma_i32_16x16x64_i8 v[80:83], v[194:197], v[218:221], v[80:83]
	v_mfma_i32_16x16x64_i8 v[76:79], v[186:189], v[226:229], v[76:79]
	v_mfma_i32_16x16x64_i8 v[72:75], v[194:197], v[226:229], v[72:75]
	v_mfma_i32_16x16x64_i8 v[116:119], v[190:193], v[206:209], v[116:119]
	v_mfma_i32_16x16x64_i8 v[108:111], v[198:201], v[206:209], v[108:111]
	v_mfma_i32_16x16x64_i8 v[100:103], v[190:193], v[214:217], v[100:103]
	v_mfma_i32_16x16x64_i8 v[92:95], v[198:201], v[214:217], v[92:95]
	v_mfma_i32_16x16x64_i8 v[84:87], v[190:193], v[222:225], v[84:87]
	v_mfma_i32_16x16x64_i8 v[80:83], v[198:201], v[222:225], v[80:83]
	v_mfma_i32_16x16x64_i8 v[76:79], v[190:193], v[230:233], v[76:79]
	v_mfma_i32_16x16x64_i8 v[72:75], v[198:201], v[230:233], v[72:75]
	s_setprio 0
	s_barrier
	s_add_i32 s36, s74, s45
	v_lshl_add_u64 v[10:11], v[236:237], 0, s[14:15]
	s_mov_b32 m0, s36
	ds_read_b128 v[152:155], v180 offset:49152
	ds_read_b128 v[156:159], v180 offset:50176
	ds_read_b128 v[202:205], v180 offset:51200
	ds_read_b128 v[206:209], v180 offset:52224
	ds_read_b128 v[210:213], v180 offset:53248
	ds_read_b128 v[214:217], v180 offset:54272
	ds_read_b128 v[218:221], v180 offset:55296
	ds_read_b128 v[222:225], v180 offset:56320
	global_load_lds_dwordx4 v[10:11], off
	s_add_i32 m0, s36, 0x2000
	s_add_u32 s34, s34, 0x80080
	v_lshl_add_u64 v[10:11], v[238:239], 0, s[14:15]
	s_addc_u32 s35, s35, 0
	s_add_i32 s36, s75, s45
	global_load_lds_dwordx4 v[10:11], off
	v_lshl_add_u64 v[10:11], s[34:35], 0, v[138:139]
	s_mov_b32 m0, s36
	s_nop 0
	global_load_lds_dwordx4 v[10:11], off
	v_lshl_add_u64 v[10:11], s[34:35], 0, v[142:143]
	s_add_i32 m0, s36, 0x2000
	s_nop 0
	global_load_lds_dwordx4 v[10:11], off
	v_lshl_add_u64 v[10:11], v[240:241], 0, s[14:15]
	s_mov_b32 m0, s54
	s_nop 0
	global_load_lds_dwordx4 v[10:11], off
	v_lshl_add_u64 v[10:11], v[242:243], 0, s[14:15]
	s_mov_b32 m0, s55
	s_nop 0
	global_load_lds_dwordx4 v[10:11], off
	s_waitcnt vmcnt(8)
	s_waitcnt lgkmcnt(0)
	s_barrier
	s_setprio 1
	s_waitcnt lgkmcnt(0)
	v_mfma_i32_16x16x64_i8 v[68:71], v[160:163], v[152:155], v[68:71]
	v_mfma_i32_16x16x64_i8 v[64:67], v[168:171], v[152:155], v[64:67]
	v_mfma_i32_16x16x64_i8 v[60:63], v[160:163], v[202:205], v[60:63]
	v_mfma_i32_16x16x64_i8 v[56:59], v[168:171], v[202:205], v[56:59]
	v_mfma_i32_16x16x64_i8 v[48:51], v[160:163], v[210:213], v[48:51]
	v_mfma_i32_16x16x64_i8 v[40:43], v[168:171], v[210:213], v[40:43]
	v_mfma_i32_16x16x64_i8 v[32:35], v[160:163], v[218:221], v[32:35]
	v_mfma_i32_16x16x64_i8 v[24:27], v[168:171], v[218:221], v[24:27]
	v_mfma_i32_16x16x64_i8 v[68:71], v[164:167], v[156:159], v[68:71]
	v_mfma_i32_16x16x64_i8 v[64:67], v[182:185], v[156:159], v[64:67]
	v_mfma_i32_16x16x64_i8 v[60:63], v[164:167], v[206:209], v[60:63]
	v_mfma_i32_16x16x64_i8 v[56:59], v[182:185], v[206:209], v[56:59]
	v_mfma_i32_16x16x64_i8 v[48:51], v[164:167], v[214:217], v[48:51]
	v_mfma_i32_16x16x64_i8 v[40:43], v[182:185], v[214:217], v[40:43]
	v_mfma_i32_16x16x64_i8 v[32:35], v[164:167], v[222:225], v[32:35]
	v_mfma_i32_16x16x64_i8 v[24:27], v[182:185], v[222:225], v[24:27]
	s_setprio 0
	s_setprio 1
	v_mfma_i32_16x16x64_i8 v[52:55], v[186:189], v[152:155], v[52:55]
	v_mfma_i32_16x16x64_i8 v[44:47], v[194:197], v[152:155], v[44:47]
	v_mfma_i32_16x16x64_i8 v[36:39], v[186:189], v[202:205], v[36:39]
	v_mfma_i32_16x16x64_i8 v[28:31], v[194:197], v[202:205], v[28:31]
	v_mfma_i32_16x16x64_i8 v[20:23], v[186:189], v[210:213], v[20:23]
	v_mfma_i32_16x16x64_i8 v[16:19], v[194:197], v[210:213], v[16:19]
	v_mfma_i32_16x16x64_i8 v[10:13], v[186:189], v[218:221], v[12:15]
	v_mfma_i32_16x16x64_i8 v[6:9], v[194:197], v[218:221], v[6:9]
	v_mfma_i32_16x16x64_i8 v[52:55], v[190:193], v[156:159], v[52:55]
	v_mfma_i32_16x16x64_i8 v[44:47], v[198:201], v[156:159], v[44:47]
	v_mfma_i32_16x16x64_i8 v[36:39], v[190:193], v[206:209], v[36:39]
	v_mfma_i32_16x16x64_i8 v[28:31], v[198:201], v[206:209], v[28:31]
	v_mfma_i32_16x16x64_i8 v[20:23], v[190:193], v[214:217], v[20:23]
	v_mfma_i32_16x16x64_i8 v[16:19], v[198:201], v[214:217], v[16:19]
	v_mfma_i32_16x16x64_i8 v[12:15], v[190:193], v[222:225], v[10:13]
	v_mfma_i32_16x16x64_i8 v[8:11], v[198:201], v[222:225], v[6:9]
	s_setprio 0
	s_barrier
	s_add_u32 s30, s30, 0x100
	s_addc_u32 s31, s31, 0
	s_add_u32 s72, s72, 0x100
	s_addc_u32 s73, s73, 0
	s_cmp_ge_i32 s8, s66
	s_cbranch_scc0 .Lp1i_top
	s_branch .Lp1i_epi

.Lp1i_epi:
	v_cvt_f32_i32_e32 v154, v132
	v_cvt_f32_i32_e32 v155, v133
	v_cvt_f32_i32_e32 v152, v134
	v_cvt_f32_i32_e32 v153, v135
	v_cvt_f32_i32_e32 v132, v128
	v_cvt_f32_i32_e32 v133, v129
	v_cvt_f32_i32_e32 v134, v130
	v_cvt_f32_i32_e32 v135, v131
	v_cvt_f32_i32_e32 v158, v116
	v_cvt_f32_i32_e32 v159, v117
	v_cvt_f32_i32_e32 v162, v118
	v_cvt_f32_i32_e32 v163, v119
	v_cvt_f32_i32_e32 v156, v108
	v_cvt_f32_i32_e32 v157, v109
	v_cvt_f32_i32_e32 v160, v110
	v_cvt_f32_i32_e32 v161, v111
	v_cvt_f32_i32_e32 v116, v124
	v_cvt_f32_i32_e32 v117, v125
	v_cvt_f32_i32_e32 v118, v126
	v_cvt_f32_i32_e32 v119, v127
	v_cvt_f32_i32_e32 v120, v120
	v_cvt_f32_i32_e32 v121, v121
	v_cvt_f32_i32_e32 v122, v122
	v_cvt_f32_i32_e32 v123, v123
	v_cvt_f32_i32_e32 v124, v100
	v_cvt_f32_i32_e32 v125, v101
	v_cvt_f32_i32_e32 v126, v102
	v_cvt_f32_i32_e32 v127, v103
	v_cvt_f32_i32_e32 v128, v92
	v_cvt_f32_i32_e32 v129, v93
	v_cvt_f32_i32_e32 v130, v94
	v_cvt_f32_i32_e32 v131, v95
	v_cvt_f32_i32_e32 v112, v112
	v_cvt_f32_i32_e32 v113, v113
	v_cvt_f32_i32_e32 v114, v114
	v_cvt_f32_i32_e32 v115, v115
	v_cvt_f32_i32_e32 v100, v104
	v_cvt_f32_i32_e32 v101, v105
	v_cvt_f32_i32_e32 v102, v106
	v_cvt_f32_i32_e32 v103, v107
	v_cvt_f32_i32_e32 v104, v84
	v_cvt_f32_i32_e32 v105, v85
	v_cvt_f32_i32_e32 v106, v86
	v_cvt_f32_i32_e32 v107, v87
	v_cvt_f32_i32_e32 v108, v80
	v_cvt_f32_i32_e32 v109, v81
	v_cvt_f32_i32_e32 v110, v82
	v_cvt_f32_i32_e32 v111, v83
	v_cvt_f32_i32_e32 v80, v96
	v_cvt_f32_i32_e32 v81, v97
	v_cvt_f32_i32_e32 v82, v98
	v_cvt_f32_i32_e32 v83, v99
	v_cvt_f32_i32_e32 v84, v88
	v_cvt_f32_i32_e32 v85, v89
	v_cvt_f32_i32_e32 v86, v90
	v_cvt_f32_i32_e32 v87, v91
	v_cvt_f32_i32_e32 v90, v76
	v_cvt_f32_i32_e32 v91, v77
	v_cvt_f32_i32_e32 v92, v78
	v_cvt_f32_i32_e32 v93, v79
	v_cvt_f32_i32_e32 v94, v72
	v_cvt_f32_i32_e32 v95, v73
	v_cvt_f32_i32_e32 v96, v74
	v_cvt_f32_i32_e32 v97, v75
	v_cvt_f32_i32_e32 v68, v68
	v_cvt_f32_i32_e32 v69, v69
	v_cvt_f32_i32_e32 v70, v70
	v_cvt_f32_i32_e32 v71, v71
	v_cvt_f32_i32_e32 v72, v64
	v_cvt_f32_i32_e32 v73, v65
	v_cvt_f32_i32_e32 v66, v66
	v_cvt_f32_i32_e32 v67, v67
	v_cvt_f32_i32_e32 v74, v52
	v_cvt_f32_i32_e32 v75, v53
	v_cvt_f32_i32_e32 v76, v54
	v_cvt_f32_i32_e32 v77, v55
	v_cvt_f32_i32_e32 v78, v44
	v_cvt_f32_i32_e32 v79, v45
	v_cvt_f32_i32_e32 v88, v46
	v_cvt_f32_i32_e32 v89, v47
	v_cvt_f32_i32_e32 v46, v60
	v_cvt_f32_i32_e32 v47, v61
	v_cvt_f32_i32_e32 v52, v62
	v_cvt_f32_i32_e32 v53, v63
	v_cvt_f32_i32_e32 v54, v56
	v_cvt_f32_i32_e32 v55, v57
	v_cvt_f32_i32_e32 v56, v58
	v_cvt_f32_i32_e32 v57, v59
	v_cvt_f32_i32_e32 v58, v36
	v_cvt_f32_i32_e32 v59, v37
	v_cvt_f32_i32_e32 v60, v38
	v_cvt_f32_i32_e32 v61, v39
	v_cvt_f32_i32_e32 v62, v28
	v_cvt_f32_i32_e32 v63, v29
	v_cvt_f32_i32_e32 v64, v30
	v_cvt_f32_i32_e32 v65, v31
	v_cvt_f32_i32_e32 v28, v48
	v_cvt_f32_i32_e32 v29, v49
	v_cvt_f32_i32_e32 v30, v50
	v_cvt_f32_i32_e32 v31, v51
	v_cvt_f32_i32_e32 v36, v40
	v_cvt_f32_i32_e32 v37, v41
	v_cvt_f32_i32_e32 v38, v42
	v_cvt_f32_i32_e32 v39, v43
	v_cvt_f32_i32_e32 v40, v20
	v_cvt_f32_i32_e32 v41, v21
	v_cvt_f32_i32_e32 v22, v22
	v_cvt_f32_i32_e32 v23, v23
	v_cvt_f32_i32_e32 v42, v16
	v_cvt_f32_i32_e32 v43, v17
	v_cvt_f32_i32_e32 v44, v18
	v_cvt_f32_i32_e32 v45, v19
	v_cvt_f32_i32_e32 v6, v32
	v_cvt_f32_i32_e32 v7, v33
	v_cvt_f32_i32_e32 v16, v34
	v_cvt_f32_i32_e32 v17, v35
	v_cvt_f32_i32_e32 v18, v24
	v_cvt_f32_i32_e32 v19, v25
	v_cvt_f32_i32_e32 v20, v26
	v_cvt_f32_i32_e32 v21, v27
	v_cvt_f32_i32_e32 v12, v12
	v_cvt_f32_i32_e32 v13, v13
	v_cvt_f32_i32_e32 v14, v14
	v_cvt_f32_i32_e32 v15, v15
	v_cvt_f32_i32_e32 v8, v8
	v_cvt_f32_i32_e32 v9, v9
	v_cvt_f32_i32_e32 v10, v10
	v_cvt_f32_i32_e32 v11, v11
	s_and_b64 vcc, exec, s[16:17]
	s_cbranch_vccz .LBB0_330

.Lp4_body:
	s_add_i32 s8, s71, 2
	s_add_u32 s28, s26, 0xfff00080
	s_addc_u32 s29, s27, -1
	s_cmp_eq_u32 s68, s71
	s_cselect_b32 s31, s64, s29
	s_cselect_b32 s30, s65, s28
	s_cselect_b32 s29, s66, s70
	s_cselect_b32 s28, s67, s69
	v_add_u32_e32 v5, s53, v163
	ds_read_b128 v[172:175], v5
	ds_read_b128 v[176:179], v5 offset:1024
	ds_read_b128 v[180:183], v5 offset:2048
	ds_read_b128 v[184:187], v5 offset:3072
	v_add_u32_e32 v5, s54, v163
	ds_read_b128 v[188:191], v5
	ds_read_b128 v[192:195], v5 offset:1024
	ds_read_b128 v[196:199], v5 offset:2048
	ds_read_b128 v[200:203], v5 offset:3072
	v_lshl_add_u64 v[6:7], s[26:27], 0, v[146:147]
	s_add_i32 m0, s43, 0xc000
	ds_read_b128 v[204:207], v166
	ds_read_b128 v[208:211], v166 offset:1024
	ds_read_b128 v[212:215], v166 offset:2048
	ds_read_b128 v[216:219], v166 offset:3072
	ds_read_b128 v[220:223], v166 offset:4096
	ds_read_b128 v[224:227], v166 offset:5120
	ds_read_b128 v[236:239], v166 offset:6144
	ds_read_b128 v[240:243], v166 offset:7168
	global_load_lds_dwordx4 v[6:7], off
	v_lshl_add_u64 v[6:7], s[26:27], 0, v[148:149]
	s_add_i32 m0, s43, 0xe000
	s_nop 0
	global_load_lds_dwordx4 v[6:7], off
	s_waitcnt vmcnt(8)
	s_waitcnt lgkmcnt(0)
	s_barrier
	s_setprio 1
	s_waitcnt lgkmcnt(0)
	v_mfma_f32_16x16x32_bf16 v[132:135], v[172:175], v[204:207], v[132:135]
	v_mfma_f32_16x16x32_bf16 v[128:131], v[180:183], v[204:207], v[128:131]
	v_mfma_f32_16x16x32_bf16 v[116:119], v[172:175], v[212:215], v[116:119]
	v_mfma_f32_16x16x32_bf16 v[112:115], v[180:183], v[212:215], v[112:115]
	v_mfma_f32_16x16x32_bf16 v[100:103], v[172:175], v[220:223], v[100:103]
	v_mfma_f32_16x16x32_bf16 v[96:99], v[180:183], v[220:223], v[96:99]
	v_mfma_f32_16x16x32_bf16 v[84:87], v[172:175], v[236:239], v[84:87]
	v_mfma_f32_16x16x32_bf16 v[80:83], v[180:183], v[236:239], v[80:83]
	v_mfma_f32_16x16x32_bf16 v[132:135], v[176:179], v[208:211], v[132:135]
	v_mfma_f32_16x16x32_bf16 v[128:131], v[184:187], v[208:211], v[128:131]
	v_mfma_f32_16x16x32_bf16 v[116:119], v[176:179], v[216:219], v[116:119]
	v_mfma_f32_16x16x32_bf16 v[112:115], v[184:187], v[216:219], v[112:115]
	v_mfma_f32_16x16x32_bf16 v[100:103], v[176:179], v[224:227], v[100:103]
	v_mfma_f32_16x16x32_bf16 v[96:99], v[184:187], v[224:227], v[96:99]
	v_mfma_f32_16x16x32_bf16 v[84:87], v[176:179], v[240:243], v[84:87]
	v_mfma_f32_16x16x32_bf16 v[80:83], v[184:187], v[240:243], v[80:83]
	s_setprio 0
	s_setprio 1
	v_mfma_f32_16x16x32_bf16 v[124:127], v[188:191], v[204:207], v[124:127]
	v_mfma_f32_16x16x32_bf16 v[120:123], v[196:199], v[204:207], v[120:123]
	v_mfma_f32_16x16x32_bf16 v[108:111], v[188:191], v[212:215], v[108:111]
	v_mfma_f32_16x16x32_bf16 v[104:107], v[196:199], v[212:215], v[104:107]
	v_mfma_f32_16x16x32_bf16 v[92:95], v[188:191], v[220:223], v[92:95]
	v_mfma_f32_16x16x32_bf16 v[88:91], v[196:199], v[220:223], v[88:91]
	v_mfma_f32_16x16x32_bf16 v[76:79], v[188:191], v[236:239], v[76:79]
	v_mfma_f32_16x16x32_bf16 v[72:75], v[196:199], v[236:239], v[72:75]
	v_mfma_f32_16x16x32_bf16 v[124:127], v[192:195], v[208:211], v[124:127]
	v_mfma_f32_16x16x32_bf16 v[120:123], v[200:203], v[208:211], v[120:123]
	v_mfma_f32_16x16x32_bf16 v[108:111], v[192:195], v[216:219], v[108:111]
	v_mfma_f32_16x16x32_bf16 v[104:107], v[200:203], v[216:219], v[104:107]
	v_mfma_f32_16x16x32_bf16 v[92:95], v[192:195], v[224:227], v[92:95]
	v_mfma_f32_16x16x32_bf16 v[88:91], v[200:203], v[224:227], v[88:91]
	v_mfma_f32_16x16x32_bf16 v[76:79], v[192:195], v[240:243], v[76:79]
	v_mfma_f32_16x16x32_bf16 v[72:75], v[200:203], v[240:243], v[72:75]
	s_setprio 0
	s_barrier
	s_add_i32 s71, s53, s40
	v_lshl_add_u64 v[156:157], s[28:29], 0, v[138:139]
	s_mov_b32 m0, s71
	ds_read_b128 v[204:207], v166 offset:16384
	ds_read_b128 v[208:211], v166 offset:17408
	ds_read_b128 v[212:215], v166 offset:18432
	ds_read_b128 v[216:219], v166 offset:19456
	ds_read_b128 v[220:223], v166 offset:20480
	ds_read_b128 v[224:227], v166 offset:21504
	ds_read_b128 v[236:239], v166 offset:22528
	ds_read_b128 v[240:243], v166 offset:23552
	global_load_lds_dwordx4 v[156:157], off
	s_add_i32 m0, s71, 0x2000
	s_add_u32 s72, s28, 0x100000
	v_lshl_add_u64 v[244:245], s[28:29], 0, v[142:143]
	s_addc_u32 s73, s29, 0
	s_add_i32 s71, s54, s40
	global_load_lds_dwordx4 v[244:245], off
	v_lshl_add_u64 v[6:7], s[72:73], 0, v[138:139]
	s_mov_b32 m0, s71
	v_lshl_add_u64 v[246:247], s[30:31], 0, v[136:137]
	global_load_lds_dwordx4 v[6:7], off
	v_lshl_add_u64 v[6:7], s[72:73], 0, v[142:143]
	s_add_i32 m0, s71, 0x2000
	v_lshl_add_u64 v[248:249], s[30:31], 0, v[140:141]
	global_load_lds_dwordx4 v[6:7], off
	s_mov_b32 m0, s43
	s_nop 0
	global_load_lds_dwordx4 v[246:247], off
	s_mov_b32 m0, s44
	s_nop 0
	global_load_lds_dwordx4 v[248:249], off
	s_waitcnt vmcnt(8)
	s_waitcnt lgkmcnt(0)
	s_barrier
	s_setprio 1
	s_waitcnt lgkmcnt(0)
	v_mfma_f32_16x16x32_bf16 v[68:71], v[172:175], v[204:207], v[68:71]
	v_mfma_f32_16x16x32_bf16 v[64:67], v[180:183], v[204:207], v[64:67]
	v_mfma_f32_16x16x32_bf16 v[52:55], v[172:175], v[212:215], v[52:55]
	v_mfma_f32_16x16x32_bf16 v[48:51], v[180:183], v[212:215], v[48:51]
	v_mfma_f32_16x16x32_bf16 v[36:39], v[172:175], v[220:223], v[36:39]
	v_mfma_f32_16x16x32_bf16 v[32:35], v[180:183], v[220:223], v[32:35]
	v_mfma_f32_16x16x32_bf16 v[20:23], v[172:175], v[236:239], v[20:23]
	v_mfma_f32_16x16x32_bf16 v[16:19], v[180:183], v[236:239], v[16:19]
	v_mfma_f32_16x16x32_bf16 v[68:71], v[176:179], v[208:211], v[68:71]
	v_mfma_f32_16x16x32_bf16 v[64:67], v[184:187], v[208:211], v[64:67]
	v_mfma_f32_16x16x32_bf16 v[52:55], v[176:179], v[216:219], v[52:55]
	v_mfma_f32_16x16x32_bf16 v[48:51], v[184:187], v[216:219], v[48:51]
	v_mfma_f32_16x16x32_bf16 v[36:39], v[176:179], v[224:227], v[36:39]
	v_mfma_f32_16x16x32_bf16 v[32:35], v[184:187], v[224:227], v[32:35]
	v_mfma_f32_16x16x32_bf16 v[20:23], v[176:179], v[240:243], v[20:23]
	v_mfma_f32_16x16x32_bf16 v[16:19], v[184:187], v[240:243], v[16:19]
	s_setprio 0
	s_setprio 1
	v_mfma_f32_16x16x32_bf16 v[60:63], v[188:191], v[204:207], v[60:63]
	v_mfma_f32_16x16x32_bf16 v[56:59], v[196:199], v[204:207], v[56:59]
	v_mfma_f32_16x16x32_bf16 v[44:47], v[188:191], v[212:215], v[44:47]
	v_mfma_f32_16x16x32_bf16 v[40:43], v[196:199], v[212:215], v[40:43]
	v_mfma_f32_16x16x32_bf16 v[28:31], v[188:191], v[220:223], v[28:31]
	v_mfma_f32_16x16x32_bf16 v[24:27], v[196:199], v[220:223], v[24:27]
	v_mfma_f32_16x16x32_bf16 v[12:15], v[188:191], v[236:239], v[12:15]
	v_mfma_f32_16x16x32_bf16 v[6:9], v[196:199], v[236:239], v[8:11]
	v_mfma_f32_16x16x32_bf16 v[60:63], v[192:195], v[208:211], v[60:63]
	v_mfma_f32_16x16x32_bf16 v[56:59], v[200:203], v[208:211], v[56:59]
	v_mfma_f32_16x16x32_bf16 v[44:47], v[192:195], v[216:219], v[44:47]
	v_mfma_f32_16x16x32_bf16 v[40:43], v[200:203], v[216:219], v[40:43]
	v_mfma_f32_16x16x32_bf16 v[28:31], v[192:195], v[224:227], v[28:31]
	v_mfma_f32_16x16x32_bf16 v[24:27], v[200:203], v[224:227], v[24:27]
	v_mfma_f32_16x16x32_bf16 v[12:15], v[192:195], v[240:243], v[12:15]
	v_mfma_f32_16x16x32_bf16 v[6:9], v[200:203], v[240:243], v[6:9]
	s_setprio 0
	s_barrier
	s_add_i32 s71, 0, 0x18000
	v_add_u32_e32 v5, s71, v163
	s_add_i32 s72, 0, 0x1c000
	ds_read_b128 v[172:175], v5
	ds_read_b128 v[176:179], v5 offset:1024
	ds_read_b128 v[180:183], v5 offset:2048
	ds_read_b128 v[184:187], v5 offset:3072
	v_add_u32_e32 v5, s72, v163
	ds_read_b128 v[188:191], v5
	ds_read_b128 v[192:195], v5 offset:1024
	ds_read_b128 v[196:199], v5 offset:2048
	ds_read_b128 v[200:203], v5 offset:3072
	s_add_u32 s30, s30, 0x100000
	s_addc_u32 s31, s31, 0
	s_mov_b32 m0, s45
	v_lshl_add_u64 v[10:11], s[30:31], 0, v[136:137]
	ds_read_b128 v[204:207], v166 offset:32768
	ds_read_b128 v[208:211], v166 offset:33792
	ds_read_b128 v[212:215], v166 offset:34816
	ds_read_b128 v[216:219], v166 offset:35840
	ds_read_b128 v[220:223], v166 offset:36864
	ds_read_b128 v[224:227], v166 offset:37888
	ds_read_b128 v[236:239], v166 offset:38912
	ds_read_b128 v[240:243], v166 offset:39936
	global_load_lds_dwordx4 v[10:11], off
	v_lshl_add_u64 v[10:11], s[30:31], 0, v[140:141]
	s_mov_b32 m0, s46
	s_nop 0
	global_load_lds_dwordx4 v[10:11], off
	s_waitcnt vmcnt(8)
	s_waitcnt lgkmcnt(0)
	s_barrier
	s_setprio 1
	s_waitcnt lgkmcnt(0)
	v_mfma_f32_16x16x32_bf16 v[132:135], v[172:175], v[204:207], v[132:135]
	v_mfma_f32_16x16x32_bf16 v[128:131], v[180:183], v[204:207], v[128:131]
	v_mfma_f32_16x16x32_bf16 v[116:119], v[172:175], v[212:215], v[116:119]
	v_mfma_f32_16x16x32_bf16 v[112:115], v[180:183], v[212:215], v[112:115]
	v_mfma_f32_16x16x32_bf16 v[100:103], v[172:175], v[220:223], v[100:103]
	v_mfma_f32_16x16x32_bf16 v[96:99], v[180:183], v[220:223], v[96:99]
	v_mfma_f32_16x16x32_bf16 v[84:87], v[172:175], v[236:239], v[84:87]
	v_mfma_f32_16x16x32_bf16 v[80:83], v[180:183], v[236:239], v[80:83]
	v_mfma_f32_16x16x32_bf16 v[132:135], v[176:179], v[208:211], v[132:135]
	v_mfma_f32_16x16x32_bf16 v[128:131], v[184:187], v[208:211], v[128:131]
	v_mfma_f32_16x16x32_bf16 v[116:119], v[176:179], v[216:219], v[116:119]
	v_mfma_f32_16x16x32_bf16 v[112:115], v[184:187], v[216:219], v[112:115]
	v_mfma_f32_16x16x32_bf16 v[100:103], v[176:179], v[224:227], v[100:103]
	v_mfma_f32_16x16x32_bf16 v[96:99], v[184:187], v[224:227], v[96:99]
	v_mfma_f32_16x16x32_bf16 v[84:87], v[176:179], v[240:243], v[84:87]
	v_mfma_f32_16x16x32_bf16 v[80:83], v[184:187], v[240:243], v[80:83]
	s_setprio 0
	s_setprio 1
	v_mfma_f32_16x16x32_bf16 v[124:127], v[188:191], v[204:207], v[124:127]
	v_mfma_f32_16x16x32_bf16 v[120:123], v[196:199], v[204:207], v[120:123]
	v_mfma_f32_16x16x32_bf16 v[108:111], v[188:191], v[212:215], v[108:111]
	v_mfma_f32_16x16x32_bf16 v[104:107], v[196:199], v[212:215], v[104:107]
	v_mfma_f32_16x16x32_bf16 v[92:95], v[188:191], v[220:223], v[92:95]
	v_mfma_f32_16x16x32_bf16 v[88:91], v[196:199], v[220:223], v[88:91]
	v_mfma_f32_16x16x32_bf16 v[76:79], v[188:191], v[236:239], v[76:79]
	v_mfma_f32_16x16x32_bf16 v[72:75], v[196:199], v[236:239], v[72:75]
	v_mfma_f32_16x16x32_bf16 v[124:127], v[192:195], v[208:211], v[124:127]
	v_mfma_f32_16x16x32_bf16 v[120:123], v[200:203], v[208:211], v[120:123]
	v_mfma_f32_16x16x32_bf16 v[108:111], v[192:195], v[216:219], v[108:111]
	v_mfma_f32_16x16x32_bf16 v[104:107], v[200:203], v[216:219], v[104:107]
	v_mfma_f32_16x16x32_bf16 v[92:95], v[192:195], v[224:227], v[92:95]
	v_mfma_f32_16x16x32_bf16 v[88:91], v[200:203], v[224:227], v[88:91]
	v_mfma_f32_16x16x32_bf16 v[76:79], v[192:195], v[240:243], v[76:79]
	v_mfma_f32_16x16x32_bf16 v[72:75], v[200:203], v[240:243], v[72:75]
	s_setprio 0
	s_barrier
	s_add_i32 s30, s71, s40
	v_lshl_add_u64 v[10:11], v[156:157], 0, s[6:7]
	s_mov_b32 m0, s30
	ds_read_b128 v[152:155], v166 offset:49152
	ds_read_b128 v[168:171], v166 offset:50176
	ds_read_b128 v[204:207], v166 offset:51200
	ds_read_b128 v[208:211], v166 offset:52224
	ds_read_b128 v[212:215], v166 offset:53248
	ds_read_b128 v[216:219], v166 offset:54272
	ds_read_b128 v[220:223], v166 offset:55296
	ds_read_b128 v[224:227], v166 offset:56320
	global_load_lds_dwordx4 v[10:11], off
	s_add_i32 m0, s30, 0x2000
	s_add_u32 s28, s28, 0x100080
	v_lshl_add_u64 v[10:11], v[244:245], 0, s[6:7]
	s_addc_u32 s29, s29, 0
	s_add_i32 s30, s72, s40
	global_load_lds_dwordx4 v[10:11], off
	v_lshl_add_u64 v[10:11], s[28:29], 0, v[138:139]
	s_mov_b32 m0, s30
	s_nop 0
	global_load_lds_dwordx4 v[10:11], off
	v_lshl_add_u64 v[10:11], s[28:29], 0, v[142:143]
	s_add_i32 m0, s30, 0x2000
	s_nop 0
	global_load_lds_dwordx4 v[10:11], off
	v_lshl_add_u64 v[10:11], v[246:247], 0, s[6:7]
	s_mov_b32 m0, s49
	s_nop 0
	global_load_lds_dwordx4 v[10:11], off
	v_lshl_add_u64 v[10:11], v[248:249], 0, s[6:7]
	s_mov_b32 m0, s50
	s_nop 0
	global_load_lds_dwordx4 v[10:11], off
	s_waitcnt vmcnt(8)
	s_waitcnt lgkmcnt(0)
	s_barrier
	s_setprio 1
	s_waitcnt lgkmcnt(0)
	v_mfma_f32_16x16x32_bf16 v[68:71], v[172:175], v[152:155], v[68:71]
	v_mfma_f32_16x16x32_bf16 v[64:67], v[180:183], v[152:155], v[64:67]
	v_mfma_f32_16x16x32_bf16 v[52:55], v[172:175], v[204:207], v[52:55]
	v_mfma_f32_16x16x32_bf16 v[48:51], v[180:183], v[204:207], v[48:51]
	v_mfma_f32_16x16x32_bf16 v[36:39], v[172:175], v[212:215], v[36:39]
	v_mfma_f32_16x16x32_bf16 v[32:35], v[180:183], v[212:215], v[32:35]
	v_mfma_f32_16x16x32_bf16 v[20:23], v[172:175], v[220:223], v[20:23]
	v_mfma_f32_16x16x32_bf16 v[16:19], v[180:183], v[220:223], v[16:19]
	v_mfma_f32_16x16x32_bf16 v[68:71], v[176:179], v[168:171], v[68:71]
	v_mfma_f32_16x16x32_bf16 v[64:67], v[184:187], v[168:171], v[64:67]
	v_mfma_f32_16x16x32_bf16 v[52:55], v[176:179], v[208:211], v[52:55]
	v_mfma_f32_16x16x32_bf16 v[48:51], v[184:187], v[208:211], v[48:51]
	v_mfma_f32_16x16x32_bf16 v[36:39], v[176:179], v[216:219], v[36:39]
	v_mfma_f32_16x16x32_bf16 v[32:35], v[184:187], v[216:219], v[32:35]
	v_mfma_f32_16x16x32_bf16 v[20:23], v[176:179], v[224:227], v[20:23]
	v_mfma_f32_16x16x32_bf16 v[16:19], v[184:187], v[224:227], v[16:19]
	s_setprio 0
	s_setprio 1
	v_mfma_f32_16x16x32_bf16 v[60:63], v[188:191], v[152:155], v[60:63]
	v_mfma_f32_16x16x32_bf16 v[56:59], v[196:199], v[152:155], v[56:59]
	v_mfma_f32_16x16x32_bf16 v[44:47], v[188:191], v[204:207], v[44:47]
	v_mfma_f32_16x16x32_bf16 v[40:43], v[196:199], v[204:207], v[40:43]
	v_mfma_f32_16x16x32_bf16 v[28:31], v[188:191], v[212:215], v[28:31]
	v_mfma_f32_16x16x32_bf16 v[24:27], v[196:199], v[212:215], v[24:27]
	v_mfma_f32_16x16x32_bf16 v[10:13], v[188:191], v[220:223], v[12:15]
	v_mfma_f32_16x16x32_bf16 v[6:9], v[196:199], v[220:223], v[6:9]
	v_mfma_f32_16x16x32_bf16 v[60:63], v[192:195], v[168:171], v[60:63]
	v_mfma_f32_16x16x32_bf16 v[56:59], v[200:203], v[168:171], v[56:59]
	v_mfma_f32_16x16x32_bf16 v[44:47], v[192:195], v[208:211], v[44:47]
	v_mfma_f32_16x16x32_bf16 v[40:43], v[200:203], v[208:211], v[40:43]
	v_mfma_f32_16x16x32_bf16 v[28:31], v[192:195], v[216:219], v[28:31]
	v_mfma_f32_16x16x32_bf16 v[24:27], v[200:203], v[216:219], v[24:27]
	v_mfma_f32_16x16x32_bf16 v[12:15], v[192:195], v[224:227], v[10:13]
	v_mfma_f32_16x16x32_bf16 v[8:11], v[200:203], v[224:227], v[6:9]
	s_setprio 0
	s_barrier
	s_add_u32 s26, s26, 0x100
	s_addc_u32 s27, s27, 0
	s_add_u32 s69, s69, 0x100
	s_addc_u32 s70, s70, 0
	s_cmp_ge_i32 s8, s63
	s_cbranch_scc0 .Lp4_top
	s_branch .Lp4_epi

.Lp4_epi:
	v_readlane_b32 s64, v254, 26
	v_readlane_b32 s65, v254, 27
	s_and_b64 vcc, exec, s[10:11]
	s_cbranch_vccz .LBB0_1036
